# m7 plus: scan hw0 U/dl prefetch moved into the FILL_A section (role balancing), waited at the next chunk top
# baseline (speedup 1.0000x reference)
.LBB0_862:
	s_add_i32 s47, s47, 64
	s_add_i32 s48, s48, 8
	s_add_i32 s70, s70, 1
	v_lshl_add_u64 v[166:167], v[166:167], 0, s[40:41]
	v_lshl_add_u64 v[168:169], v[168:169], 0, s[42:43]
	s_cmpk_lg_i32 s47, 0x800
	s_cbranch_scc0 .LBB0_823
.LBB0_863:
	s_cmp_eq_u32 s70, 0
	s_cbranch_scc1 .Lmy_scan_t0
	s_cmp_lt_u32 s70, 31
	s_cbranch_scc1 .Lmy_scan_t5
	s_waitcnt vmcnt(0)
	s_branch .Lmy_scan_tj
.Lmy_scan_t5:
	s_waitcnt vmcnt(9)
.Lmy_scan_tj:
	v_mov_b32_e32 v120, v207

.LBB0_874:
	s_or_b64 exec, exec, s[52:53]
	ds_read_b128 v[214:217], v183 offset:44032
	ds_read_b128 v[218:221], v183 offset:48640
	s_cmp_lg_u32 s70, 0
	s_cbranch_scc1 .Lmy_scan_w10
	s_waitcnt vmcnt(9)

.LBB0_880:
	s_or_b64 exec, exec, s[52:53]
	ds_read_b128 v[116:119], v183 offset:44128
	ds_read_b128 v[214:217], v183 offset:48736
	s_and_b64 vcc, exec, s[50:51]
	s_waitcnt lgkmcnt(1)
	v_mfma_f32_32x32x16_bf16 v[0:15], v[116:119], v[120:123], v[0:15]
	s_waitcnt lgkmcnt(0)
	v_mfma_f32_32x32x16_bf16 v[16:31], v[214:217], v[120:123], v[16:31]
	s_cbranch_vccz .LBB0_899
	s_waitcnt vmcnt(8)
	ds_write_b128 v129, v[80:83]
	s_waitcnt vmcnt(7)
	ds_write_b128 v173, v[84:87]
	s_waitcnt vmcnt(6)
	ds_write_b128 v174, v[92:95]
	s_waitcnt vmcnt(5)
	ds_write_b128 v175, v[104:107]
	s_and_saveexec_b64 s[52:53], s[10:11]
	s_cbranch_execz .LBB0_868
	v_add_u32_e32 v230, s47, v205
	v_mov_b64_e32 v[232:233], s[18:19]
	v_mad_i64_i32 v[232:233], s[34:35], v230, s60, v[232:233]
	v_lshl_add_u64 v[232:233], v[232:233], 0, s[36:37]
	v_lshl_add_u64 v[232:233], v[232:233], 0, v[124:125]
	v_lshlrev_b32_e32 v230, 1, v148
	v_mov_b32_e32 v231, v125
	v_lshl_add_u64 v[232:233], v[232:233], 0, v[230:231]
	v_lshl_add_u64 v[230:231], v[232:233], 0, s[38:39]
	v_add_co_u32_e32 v232, vcc, 0x1000, v232
	s_nop 1
	v_addc_co_u32_e32 v233, vcc, 0, v233, vcc
	global_load_dwordx2 v[132:133], v[230:231], off offset:64
	global_load_dwordx2 v[130:131], v[230:231], off offset:16
	global_load_dwordx2 v[134:135], v[230:231], off offset:32
	global_load_dwordx2 v[138:139], v[230:231], off offset:48
	global_load_dwordx2 v[136:137], v[232:233], off
	global_load_dwordx2 v[140:141], v[230:231], off offset:80
	global_load_dwordx2 v[142:143], v[230:231], off offset:96
	global_load_dwordx2 v[144:145], v[230:231], off offset:112
.LBB0_868:
	s_or_b64 exec, exec, s[52:53]
	s_add_i32 s34, s48, -8
	s_ashr_i32 s35, s34, 31
	s_lshl_b64 s[34:35], s[34:35], 2
	s_add_u32 s34, s28, s34
	s_addc_u32 s35, s29, s35
	global_load_dword v207, v125, s[34:35]
.Lmy_scan_faj:
	s_cmp_lt_u32 s70, 30
	s_cbranch_scc0 .LBB0_899
	global_load_dwordx4 v[80:83], v[222:223], off
	global_load_dwordx4 v[84:87], v[224:225], off
	global_load_dwordx4 v[92:95], v[226:227], off
	global_load_dwordx4 v[104:107], v[228:229], off
	v_lshl_add_u64 v[222:223], v[222:223], 0, s[42:43]
	v_lshl_add_u64 v[224:225], v[224:225], 0, s[42:43]
	v_lshl_add_u64 v[226:227], v[226:227], 0, s[40:41]
	v_lshl_add_u64 v[228:229], v[228:229], 0, s[40:41]

.Lmy_scan_w4:
	s_cmp_lg_u64 s[10:11], 0
	s_cbranch_scc1 .Lmy_scan_w13
	s_waitcnt vmcnt(5)
	s_branch .Lmy_scan_wj
.Lmy_scan_w13:
	s_waitcnt vmcnt(13)
